# st1 + eight per-XCD prompt-diff queues (head = xcd&3, q-block parity = xcd>>2) so both maps of a pair run on the same XCD and share V tiles in L2
# speedup vs baseline: 1.0169x; 1.0030x over previous
; template <int KIND>
; __device__ __forceinline__ void attn_queue(const AttnCtx& C, unsigned* head, int nunits, LAS unsigned char* lds) {
;     ...
;         __syncthreads();
;         if (threadIdx.x == 0) slot[0] = __hip_atomic_fetch_add(head, 1u, __ATOMIC_RELAXED, __HIP_MEMORY_SCOPE_AGENT);
.LBB0_449:
	s_waitcnt lgkmcnt(0)
	s_barrier
	s_mov_b64 s[2:3], exec
	v_readlane_b32 s0, v253, 26
	v_readlane_b32 s1, v253, 27
	s_and_b64 s[0:1], s[2:3], s[0:1]
	s_mov_b64 exec, s[0:1]
	s_cbranch_execz .LBB0_453
	s_mov_b64 s[6:7], exec
	v_mbcnt_lo_u32_b32 v2, s6, 0
	v_mbcnt_hi_u32_b32 v2, s7, v2
	v_cmp_eq_u32_e32 vcc, 0, v2
	s_and_saveexec_b64 s[4:5], vcc
	s_cbranch_execz .LBB0_452
	v_readlane_b32 s0, v253, 2
	s_and_b32 s0, s0, 7
	s_lshl_b32 s0, s0, 8
	s_add_i32 s0, s0, 0x18000
	v_mov_b32_e32 v254, s0
	s_bcnt1_i32_b64 s0, s[6:7]
	v_mov_b32_e32 v4, s0
	global_atomic_add v4, v254, v4, s[94:95] sc0

; template <bool NOMAX>
; __device__ __forceinline__ void diff_unit(const AttnCtx& C, int u, LAS unsigned char* lds) {
;     int tid = threadIdx.x; asm volatile("" : "+v"(tid));
;     const int lane = tid & 63, r32 = lane & 31, hi = lane >> 5; const int wid = __builtin_amdgcn_readfirstlane(tid >> 6);
;     const int umap = (u >> 2) & 1, h = u & 3, qb = 63 - (u >> 3);
;     const int n = 4 * qb + 4, q0 = 256 * qb;
;     LAS float* wsf = (LAS float*)(lds + TD_WS) + wid * 64;
;     const LAS float* tab = (const LAS float*)(lds + AL_TAB) + h * 192;
;     const float c15 = tab[0];
;     const int qrel = wid * 32 + r32, qpos = q0 + qrel;
;     const int tmax = n - 4 + (wid >> 1);
;     __syncthreads();
;     const bf16* Qw = C.DQ + (size_t)(q0 + wid * 32) * 512 + h * 128 + umap * 64;
;     const bf16* Kh = C.DK + h * 128 + umap * 64; const bf16* Vh = C.DV + h * 128;
;     const unsigned lds0 = (unsigned)(size_t)lds;
;     const bf16* ksrc = Kh + (size_t)lane * 512 + wid * 8;
;     const bf16* vsrc = Vh + (size_t)(16 * (wid & 3) + (lane >> 2)) * 512 + (wid >> 2) * 32 + (lane & 3) * 8;
;     const unsigned kdst = lds0 + TD_K + wid * 1024, vdst = lds0 + TD_V + wid * 1024;
;     ...
;     const lcp kp0 = (lcp)(lds + TD_K) + hi * 1024 + r32 * 16;
;     const lcp vp0 = (lcp)(lds + TD_V) + ((lane >> 4) & 1) * 32 + (lane & 3) * 8 + (4 * hi + ((lane & 15) >> 2)) * 64;
;     bf16x8 kf[8];
;     DMA_K(0, 0); DMA_V(0, 0); DMA_K(1, SLOTB);
;     const lcp qp0 = (lcp)(lds + TD_Q) + wid * 4096 + lane * 16;
;     {
;         bf16x8 qr[4];
; #pragma unroll
;         for (int d0 = 0; d0 < 4; ++d0) qr[d0] = *(const bf16x8*)(Qw + (size_t)r32 * 512 + d0 * 16 + hi * 8);
; #pragma unroll
;         for (int d0 = 0; d0 < 4; ++d0) *(LAS bf16x8*)((LAS unsigned char*)qp0 + d0 * 1024) = qr[d0];
;     }
;     ...
;     float nm = c15, l_reg = 0.f;
;     f32x16 o[4];
; #pragma unroll
;     for (int d = 0; d < 4; ++d) o[d] = (f32x16){0.f,0.f,0.f,0.f,0.f,0.f,0.f,0.f,0.f,0.f,0.f,0.f,0.f,0.f,0.f,0.f};
;     bool resc = false;
;     ...
;     f32x16 pA0, pA1, pB0, pB1;
;     const f32x16 ZERO16 = (f32x16){0.f,0.f,0.f,0.f,0.f,0.f,0.f,0.f,0.f,0.f,0.f,0.f,0.f,0.f,0.f,0.f};
;     int sl_prev = 0, sl_cur = 0, sl_next = 1;
;     ...
;     DMA_K(2, 2 * SLOTB);
;     TWAIT_BAR(4);
;     {
;         if constexpr (NOMAX) { pA0 = (f32x16){0.f,0.f,0.f,0.f,0.f,0.f,0.f,0.f,0.f,0.f,0.f,0.f,0.f,0.f,0.f,0.f}; pA1 = pA0; } else { INITC(pA0, pA1); }
.LBB0_453:
	s_or_b64 exec, exec, s[2:3]
	s_waitcnt lgkmcnt(0)
	s_barrier
	ds_read_b32 v2, v1
	s_movk_i32 s0, 0x3f
	s_mov_b64 s[2:3], -1
	s_waitcnt lgkmcnt(0)
	v_cmp_lt_u32_e32 vcc, s0, v2
	s_cbranch_vccnz .LBB0_448
	v_readlane_b32 s0, v253, 2
	s_and_b32 s0, s0, 7
	s_lshr_b32 s1, s0, 2
	s_lshl_b32 s1, s1, 3
	s_and_b32 s0, s0, 3
	s_or_b32 s0, s0, s1
	v_lshrrev_b32_e32 v254, 1, v2
	v_and_b32_e32 v2, 1, v2
	v_lshlrev_b32_e32 v2, 2, v2
	v_lshl_or_b32 v2, v254, 4, v2
	v_or_b32_e32 v2, s0, v2
	v_lshlrev_b32_e32 v4, 1, v2
	v_and_b32_e32 v4, 6, v4
	v_bfe_u32 v230, v2, 2, 1
	v_and_b32_e32 v231, 3, v2
	s_movk_i32 s0, 0x300
	v_or_b32_e32 v4, v4, v230
	v_lshrrev_b32_e32 v7, 3, v2
	v_mul_lo_u32 v2, v231, s0
	v_readlane_b32 s0, v253, 56
	v_lshrrev_b32_e32 v4, v4, v233
	v_lshlrev_b32_e32 v220, 8, v231
	v_mov_b32_e32 v221, v3
	v_readlane_b32 s1, v253, 57
	v_and_b32_e32 v6, 1, v4
	v_add_u32_e32 v2, 0, v2
	v_lshl_add_u64 v[4:5], s[0:1], 0, v[220:221]
	v_readlane_b32 s0, v253, 58
	v_xor_b32_e32 v224, 63, v7
	v_add_u32_e32 v235, 0x20400, v2
	v_lshlrev_b32_e32 v8, 7, v231
	v_lshlrev_b32_e32 v9, 6, v230
	v_lshlrev_b32_e32 v2, 7, v230
	v_readlane_b32 s1, v253, 59
	v_cmp_eq_u32_e32 vcc, 0, v6
	v_lshlrev_b32_e32 v234, 2, v224
	v_lshlrev_b32_e32 v19, 8, v224
	v_lshl_add_u64 v[198:199], v[4:5], 0, v[2:3]
	v_lshl_add_u64 v[196:197], s[0:1], 0, v[220:221]
	v_cmp_ne_u32_e64 s[2:3], 63, v7
	v_lshlrev_b32_e32 v218, 1, v8
	v_lshlrev_b32_e32 v200, 1, v9
	s_cbranch_vccnz .LBB0_465
	v_mov_b32_e32 v6, v0
	v_readlane_b32 s4, v253, 54
	v_readfirstlane_b32 s1, v6
	s_ashr_i32 s6, s1, 6
	s_lshl_b32 s33, s6, 5
	v_add_u32_e32 v202, s33, v19
	v_ashrrev_i32_e32 v203, 31, v202
	v_lshlrev_b64 v[4:5], 10, v[202:203]
	v_readlane_b32 s5, v253, 55
	v_and_b32_e32 v212, 63, v6
	v_mov_b32_e32 v219, v3
	v_lshl_add_u64 v[4:5], s[4:5], 0, v[4:5]
	v_lshl_add_u64 v[4:5], v[4:5], 0, v[218:219]
	v_mov_b32_e32 v201, v3
	v_lshlrev_b32_e32 v2, 10, v212
	s_lshl_b32 s0, s6, 4
	v_bfe_u32 v208, v6, 2, 4
	v_lshl_add_u64 v[8:9], v[4:5], 0, v[200:201]
	v_lshl_add_u64 v[4:5], v[198:199], 0, v[2:3]
	s_lshl_b32 s4, s6, 3
	v_and_or_b32 v2, s0, 48, v208
	s_ashr_i32 s5, s4, 31
	v_lshlrev_b32_e32 v2, 10, v2
	s_ashr_i32 s0, s1, 3
	v_lshl_add_u64 v[204:205], s[4:5], 1, v[4:5]
	v_lshl_add_u64 v[4:5], v[196:197], 0, v[2:3]
	s_and_b32 s4, s0, 0xffffffe0
	v_lshlrev_b32_e32 v2, 3, v6
	s_ashr_i32 s5, s4, 31
	v_and_b32_e32 v7, 24, v2
	s_lshl_b32 s49, s6, 10
	v_and_b32_e32 v210, 31, v6
	ds_read_b32 v213, v235
	s_waitcnt lgkmcnt(0)
	s_barrier
	v_lshl_add_u64 v[4:5], s[4:5], 1, v[4:5]
	v_lshlrev_b32_e32 v2, 1, v7
	s_add_i32 s49, s49, 0
	s_mov_b32 s0, m0
	s_mov_b32 m0, s49
	s_nop 0
	global_load_lds_dwordx4 v[204:205], off
	s_mov_b32 m0, s0
	v_bfe_u32 v211, v6, 5, 1
	v_lshl_add_u64 v[4:5], v[4:5], 0, v[2:3]
	s_add_i32 s58, s49, 0x6000
	s_mov_b32 s0, m0
	s_mov_b32 m0, s58
	s_nop 0
	global_load_lds_dwordx4 v[4:5], off
	s_mov_b32 m0, s0
	v_lshlrev_b32_e32 v2, 10, v210
	v_lshl_add_u64 v[10:11], v[4:5], 0, s[18:19]
	s_add_i32 s0, s49, 0x8000
	s_mov_b32 s7, m0
	s_mov_b32 m0, s0
	s_nop 0
	global_load_lds_dwordx4 v[10:11], off
	s_mov_b32 m0, s7
	v_lshl_add_u64 v[8:9], v[8:9], 0, v[2:3]
	v_lshlrev_b32_e32 v2, 4, v211
	v_lshl_add_u64 v[10:11], v[204:205], 0, s[20:21]
	s_add_i32 s0, s49, 0x2000
	s_mov_b32 s7, m0
	s_mov_b32 m0, s0
	s_nop 0
	global_load_lds_dwordx4 v[10:11], off
	s_mov_b32 m0, s7
	v_lshl_add_u64 v[16:17], v[8:9], 0, v[2:3]
	global_load_dwordx4 v[8:11], v[16:17], off
	global_load_dwordx4 v[12:15], v[16:17], off offset:32
	global_load_dwordx4 v[20:23], v[16:17], off offset:64
	global_load_dwordx4 v[24:27], v[16:17], off offset:96
	s_lshl_b32 s0, s6, 12
	s_add_i32 s7, s0, 0
	v_lshlrev_b32_e32 v16, 4, v212
	s_add_i32 s7, s7, 0x12800
	v_add_u32_e32 v219, s7, v16
	v_lshlrev_b32_e32 v201, 10, v211
	v_lshlrev_b32_e32 v2, 4, v210
	s_add_i32 s8, s49, 0x4000
	v_lshl_add_u64 v[16:17], v[204:205], 0, s[22:23]
	v_add3_u32 v222, 0, v201, v2
	s_ashr_i32 s48, s1, 7
	v_or_b32_e32 v2, s33, v210
	s_and_b64 vcc, exec, s[2:3]
	v_add_u32_e32 v223, s48, v234
	v_add_u32_e32 v215, v2, v19
	s_waitcnt vmcnt(3)
	ds_write_b128 v219, v[8:11]
	s_waitcnt vmcnt(2)
	ds_write_b128 v219, v[12:15] offset:1024
	s_waitcnt vmcnt(1)
	ds_write_b128 v219, v[20:23] offset:2048
	s_waitcnt vmcnt(0)
	ds_write_b128 v219, v[24:27] offset:3072
	s_mov_b32 s7, m0
	s_mov_b32 m0, s8
	s_nop 0
	global_load_lds_dwordx4 v[16:17], off
	s_mov_b32 m0, s7
	s_waitcnt vmcnt(4) lgkmcnt(0)
	s_barrier
	ds_read_b128 v[8:11], v222
	ds_read_b128 v[12:15], v219
	s_waitcnt lgkmcnt(0)
	v_mfma_f32_32x32x16_bf16 v[36:51], v[8:11], v[12:15], 0
	ds_read_b128 v[8:11], v222 offset:512
	s_waitcnt lgkmcnt(0)
	v_mfma_f32_32x32x16_bf16 v[20:35], v[8:11], v[12:15], 0
	ds_read_b128 v[8:11], v222 offset:2048
	ds_read_b128 v[12:15], v219 offset:1024
	s_waitcnt lgkmcnt(0)
	v_mfma_f32_32x32x16_bf16 v[36:51], v[8:11], v[12:15], v[36:51]
	ds_read_b128 v[8:11], v222 offset:2560
	s_waitcnt lgkmcnt(0)
	v_mfma_f32_32x32x16_bf16 v[20:35], v[8:11], v[12:15], v[20:35]
	ds_read_b128 v[8:11], v222 offset:4096
	ds_read_b128 v[12:15], v219 offset:2048
	s_waitcnt lgkmcnt(0)
	v_mfma_f32_32x32x16_bf16 v[36:51], v[8:11], v[12:15], v[36:51]
	ds_read_b128 v[8:11], v222 offset:4608
	s_waitcnt lgkmcnt(0)
	v_mfma_f32_32x32x16_bf16 v[20:35], v[8:11], v[12:15], v[20:35]
	ds_read_b128 v[8:11], v222 offset:6144
	ds_read_b128 v[12:15], v219 offset:3072
	s_waitcnt lgkmcnt(0)
	v_mfma_f32_32x32x16_bf16 v[36:51], v[8:11], v[12:15], v[36:51]
	ds_read_b128 v[8:11], v222 offset:6656
	s_waitcnt lgkmcnt(0)
	v_mfma_f32_32x32x16_bf16 v[20:35], v[8:11], v[12:15], v[20:35]
	s_cbranch_vccnz .LBB0_461
; #define LAS __attribute__((address_space(3)))
; #define TWAIT_BAR(N) asm volatile("s_waitcnt vmcnt(" #N ") lgkmcnt(0)\n\ts_barrier" ::: "memory")
; #define DMA_K(t, slot) glds16(ksrc + (size_t)(t) * 64 * 512, (unsigned)__builtin_amdgcn_readfirstlane(kdst + (slot)))
; #define DMA_K(t, slot) glds16(ksrc + (size_t)(t) * 64 * 512, (unsigned)__builtin_amdgcn_readfirstlane(kdst + (slot)))
; #define INITC(P0, P1) do { _Pragma("unroll") for (int r_ = 0; r_ < 16; ++r_) { P0[r_] = nm; P1[r_] = nm; } } while (0)
; #define INITC(P0, P1) do { _Pragma("unroll") for (int r_ = 0; r_ < 16; ++r_) { P0[r_] = nm; P1[r_] = nm; } } while (0)
; #define NEARK(P0, P1, kk) do { if ((kk) >= 62) _Pragma("unroll") for (int r_ = 0; r_ < 16; ++r_) { const int rel0 = (kk) * 64 + crow(r_, hi) - qpos; int i0 = rel0 < -128 ? -128 : rel0; i0 = i0 > 63 ? 63 : i0; int i1 = rel0 + 32 < -128 ? -128 : rel0 + 32; i1 = i1 > 63 ? 63 : i1; \
;             P0[r_] += tab[i0 + 128] - c15; P1[r_] += tab[i1 + 128] - c15; } } while (0)
; template <bool NOMAX>
; __device__ __forceinline__ void diff_unit(const AttnCtx& C, int u, LAS unsigned char* lds) {
;     ...
;     f32x16 pA0, pA1, pB0, pB1;
;     const f32x16 ZERO16 = (f32x16){0.f,0.f,0.f,0.f,0.f,0.f,0.f,0.f,0.f,0.f,0.f,0.f,0.f,0.f,0.f,0.f};
;     int sl_prev = 0, sl_cur = 0, sl_next = 1;
;     ...
;     DMA_K(2, 2 * SLOTB);
;     TWAIT_BAR(4);
;     {
;         if constexpr (NOMAX) { pA0 = (f32x16){0.f,0.f,0.f,0.f,0.f,0.f,0.f,0.f,0.f,0.f,0.f,0.f,0.f,0.f,0.f,0.f}; pA1 = pA0; } else { INITC(pA0, pA1); }
;         const lcp kb = kp0;
; #pragma unroll
;         for (int d0 = 0; d0 < 4; ++d0) { const bf16x8 b0 = *(const LAS bf16x8*)(kb + d0 * 2048), b1 = *(const LAS bf16x8*)(kb + d0 * 2048 + 512);
;             const bf16x8 qv = QRD(d0); pA0 = __builtin_amdgcn_mfma_f32_32x32x16_bf16(b0, qv, pA0, 0, 0, 0); pA1 = __builtin_amdgcn_mfma_f32_32x32x16_bf16(b1, qv, pA1, 0, 0, 0); }
;         NEARK(pA0, pA1, 0);
	v_cmp_gt_i32_e32 vcc, 0, v223
	v_mov_b32_e32 v2, 0xff800000
	s_and_b64 vcc, exec, vcc
	v_mov_b32_e32 v8, 0xff800000
	v_mov_b32_e32 v9, 0xff800000
	v_mov_b32_e32 v10, 0xff800000
	v_mov_b32_e32 v11, 0xff800000
	v_mov_b32_e32 v12, 0xff800000
	v_mov_b32_e32 v13, 0xff800000
	v_mov_b32_e32 v14, 0xff800000
	v_mov_b32_e32 v15, 0xff800000
	v_mov_b32_e32 v16, 0xff800000
	v_mov_b32_e32 v17, 0xff800000
	v_mov_b32_e32 v52, 0xff800000
	v_mov_b32_e32 v53, 0xff800000
	v_mov_b32_e32 v54, 0xff800000
	v_mov_b32_e32 v55, 0xff800000
	v_mov_b32_e32 v56, 0xff800000
	v_mov_b32_e32 v57, 0xff800000
	v_mov_b32_e32 v58, 0xff800000
	v_mov_b32_e32 v59, 0xff800000
	v_mov_b32_e32 v60, 0xff800000
	v_mov_b32_e32 v61, 0xff800000
	v_mov_b32_e32 v62, 0xff800000
	v_mov_b32_e32 v63, 0xff800000
	v_mov_b32_e32 v64, 0xff800000
	v_mov_b32_e32 v65, 0xff800000
	v_mov_b32_e32 v66, 0xff800000
	v_mov_b32_e32 v67, 0xff800000
	v_mov_b32_e32 v68, 0xff800000
	v_mov_b32_e32 v69, 0xff800000
	v_mov_b32_e32 v70, 0xff800000
	v_mov_b32_e32 v71, 0xff800000
	v_mov_b32_e32 v72, 0xff800000
	s_cbranch_vccnz .LBB0_460
	s_cmp_gt_i32 s6, 5
	s_cbranch_scc1 .LBB0_459
	v_lshlrev_b32_e32 v2, 2, v211
	v_sub_u32_e32 v2, v2, v215
	v_add_u32_e32 v10, 1, v2
	v_add_u32_e32 v12, 2, v2
	v_add_u32_e32 v14, 3, v2
	v_med3_i32 v8, v2, s51, 63
	v_med3_i32 v9, v2, s52, 31
	v_med3_i32 v11, v10, s51, 63
	v_med3_i32 v10, v10, s52, 31
	v_med3_i32 v13, v12, s51, 63
	v_med3_i32 v12, v12, s52, 31
	v_med3_i32 v15, v14, s51, 63
	v_med3_i32 v14, v14, s52, 31
	v_lshl_add_u32 v8, v8, 2, v235
	v_lshl_add_u32 v9, v9, 2, v235
	v_lshl_add_u32 v11, v11, 2, v235
	v_lshl_add_u32 v10, v10, 2, v235
	v_lshl_add_u32 v12, v12, 2, v235
	v_lshl_add_u32 v14, v14, 2, v235
	v_lshl_add_u32 v13, v13, 2, v235
	v_lshl_add_u32 v15, v15, 2, v235
	ds_read_b32 v8, v8 offset:512
	ds_read_b32 v58, v9 offset:640
	ds_read_b32 v9, v11 offset:512
	ds_read_b32 v59, v10 offset:640
	ds_read_b32 v10, v13 offset:512
	ds_read_b32 v60, v12 offset:640
	ds_read_b32 v11, v15 offset:512
	ds_read_b32 v61, v14 offset:640
	v_add_u32_e32 v12, 8, v2
	v_add_u32_e32 v14, 9, v2
	v_add_u32_e32 v16, 10, v2
	v_add_u32_e32 v52, 11, v2
	v_med3_i32 v13, v12, s51, 63
	v_med3_i32 v12, v12, s52, 31
	v_med3_i32 v15, v14, s51, 63
	v_med3_i32 v14, v14, s52, 31
	v_med3_i32 v17, v16, s51, 63
	v_med3_i32 v53, v52, s51, 63
	v_lshl_add_u32 v13, v13, 2, v235
	v_lshl_add_u32 v12, v12, 2, v235
	v_lshl_add_u32 v15, v15, 2, v235
	v_lshl_add_u32 v14, v14, 2, v235
	v_med3_i32 v16, v16, s52, 31
	v_lshl_add_u32 v17, v17, 2, v235
	v_med3_i32 v52, v52, s52, 31
	v_lshl_add_u32 v53, v53, 2, v235
	v_lshl_add_u32 v16, v16, 2, v235
	v_lshl_add_u32 v52, v52, 2, v235
	ds_read_b32 v54, v13 offset:512
	ds_read_b32 v62, v12 offset:640
	ds_read_b32 v12, v15 offset:512
	ds_read_b32 v63, v14 offset:640
	ds_read_b32 v14, v17 offset:512
	ds_read_b32 v64, v16 offset:640
	ds_read_b32 v15, v53 offset:512
	ds_read_b32 v65, v52 offset:640
	v_add_u32_e32 v13, 16, v2
	v_add_u32_e32 v17, 17, v2
	v_add_u32_e32 v53, 18, v2
	v_med3_i32 v16, v13, s51, 63
	v_med3_i32 v13, v13, s52, 31
	v_med3_i32 v52, v17, s51, 63
	v_med3_i32 v55, v53, s51, 63
	v_med3_i32 v53, v53, s52, 31
	v_add_u32_e32 v56, 19, v2
	v_lshl_add_u32 v16, v16, 2, v235
	v_lshl_add_u32 v13, v13, 2, v235
	v_med3_i32 v17, v17, s52, 31
	v_lshl_add_u32 v52, v52, 2, v235
	v_lshl_add_u32 v55, v55, 2, v235
	v_lshl_add_u32 v53, v53, 2, v235
	v_med3_i32 v57, v56, s51, 63
	v_med3_i32 v56, v56, s52, 31
	v_lshl_add_u32 v17, v17, 2, v235
	v_lshl_add_u32 v57, v57, 2, v235
	v_lshl_add_u32 v56, v56, 2, v235
	ds_read_b32 v16, v16 offset:512
	ds_read_b32 v66, v13 offset:640
	ds_read_b32 v52, v52 offset:512
	ds_read_b32 v67, v17 offset:640
	ds_read_b32 v55, v55 offset:512
	ds_read_b32 v68, v53 offset:640
	ds_read_b32 v53, v57 offset:512
	ds_read_b32 v69, v56 offset:640
	v_add_u32_e32 v13, 24, v2
	v_med3_i32 v17, v13, s51, 63
	v_med3_i32 v13, v13, s52, 31
	v_lshl_add_u32 v57, v13, 2, v235
	v_add_u32_e32 v13, 25, v2
	v_lshl_add_u32 v56, v17, 2, v235
	v_med3_i32 v17, v13, s51, 63
	v_med3_i32 v13, v13, s52, 31
	v_lshl_add_u32 v71, v13, 2, v235
	v_add_u32_e32 v13, 26, v2
	v_lshl_add_u32 v70, v17, 2, v235
	v_med3_i32 v17, v13, s51, 63
	v_med3_i32 v13, v13, s52, 31
	v_add_u32_e32 v2, 27, v2
	v_lshl_add_u32 v73, v13, 2, v235
	v_med3_i32 v13, v2, s51, 63
	v_med3_i32 v2, v2, s52, 31
	v_lshl_add_u32 v2, v2, 2, v235
	v_lshl_add_u32 v72, v17, 2, v235
	v_lshl_add_u32 v74, v13, 2, v235
	s_waitcnt lgkmcnt(13)
	v_sub_f32_e32 v13, v12, v213
	v_sub_f32_e32 v12, v54, v213
	s_waitcnt lgkmcnt(5)
	v_sub_f32_e32 v17, v52, v213
	s_waitcnt lgkmcnt(3)
	v_sub_f32_e32 v52, v55, v213
	ds_read_b32 v54, v56 offset:512
	ds_read_b32 v75, v57 offset:640
	ds_read_b32 v55, v70 offset:512
	ds_read_b32 v70, v71 offset:640
	ds_read_b32 v56, v72 offset:512
	ds_read_b32 v57, v74 offset:512
	ds_read_b32 v2, v2 offset:640
	ds_read_b32 v71, v73 offset:640
	v_sub_f32_e32 v8, v8, v213
	v_sub_f32_e32 v9, v9, v213
	v_sub_f32_e32 v11, v11, v213
	v_sub_f32_e32 v10, v10, v213
	v_sub_f32_e32 v15, v15, v213
	v_sub_f32_e32 v14, v14, v213
	v_sub_f32_e32 v16, v16, v213
	s_waitcnt lgkmcnt(9)
	v_sub_f32_e32 v53, v53, v213
	s_waitcnt lgkmcnt(5)
	v_sub_f32_e32 v55, v55, v213
	v_sub_f32_e32 v54, v54, v213
	s_waitcnt lgkmcnt(2)
	v_sub_f32_e32 v57, v57, v213
	v_sub_f32_e32 v56, v56, v213
	v_pk_add_f32 v[50:51], v[50:51], v[56:57]
	v_pk_add_f32 v[48:49], v[48:49], v[54:55]
	v_pk_add_f32 v[46:47], v[46:47], v[52:53]
	v_pk_add_f32 v[44:45], v[44:45], v[16:17]
	v_pk_add_f32 v[42:43], v[42:43], v[14:15]
	v_pk_add_f32 v[40:41], v[40:41], v[12:13]
	v_pk_add_f32 v[38:39], v[38:39], v[10:11]
	v_pk_add_f32 v[36:37], v[36:37], v[8:9]
	v_sub_f32_e32 v8, v58, v213
	v_sub_f32_e32 v9, v59, v213
	v_sub_f32_e32 v11, v61, v213
	v_sub_f32_e32 v10, v60, v213
	v_sub_f32_e32 v13, v63, v213
	v_sub_f32_e32 v12, v62, v213
	v_sub_f32_e32 v15, v65, v213
	v_sub_f32_e32 v14, v64, v213
	v_sub_f32_e32 v17, v67, v213
	v_sub_f32_e32 v16, v66, v213
	v_sub_f32_e32 v53, v69, v213
	v_sub_f32_e32 v52, v68, v213
	v_sub_f32_e32 v55, v70, v213
	v_sub_f32_e32 v54, v75, v213
	s_waitcnt lgkmcnt(1)
	v_sub_f32_e32 v57, v2, v213
	s_waitcnt lgkmcnt(0)
	v_sub_f32_e32 v56, v71, v213
	v_pk_add_f32 v[34:35], v[34:35], v[56:57]
	v_pk_add_f32 v[32:33], v[32:33], v[54:55]
	v_pk_add_f32 v[30:31], v[30:31], v[52:53]
	v_pk_add_f32 v[28:29], v[28:29], v[16:17]
	v_pk_add_f32 v[26:27], v[26:27], v[14:15]
	v_pk_add_f32 v[24:25], v[24:25], v[12:13]
	v_pk_add_f32 v[22:23], v[22:23], v[10:11]
	v_pk_add_f32 v[20:21], v[20:21], v[8:9]
